# P2b combine loop: 2-deep software prefetch with scalar loop control; 64-bit moves for accumulator zeroing (P5,P6)
# baseline (speedup 1.0000x reference)
; __device__ __forceinline__ unsigned pk4_fp8(float a, float b, float c, float d) { int r = __builtin_amdgcn_cvt_pk_fp8_f32(a, b, 0, false); r = __builtin_amdgcn_cvt_pk_fp8_f32(c, d, r, true); return (unsigned)r; }
; __global__ void __launch_bounds__(512, 2) mk_fwd(Args a) {
;     ...
;     for (unsigned idx = (unsigned)bx * 512u + (unsigned)threadIdx.x; idx < (unsigned)TT * 32u; idx += (unsigned)G * 512u) {
;         const size_t tok = idx >> 5; const int part = (int)(idx & 31u), hh = part >> 3;
;         const float l0 = LSE[tok * 4 + hh], l1 = LSE[((size_t)TT + tok) * 4 + hh], l2 = LSE[((size_t)2 * TT + tok) * 4 + hh];
;         const float mx = fmaxf(l0, fmaxf(l1, l2)); float w0 = __builtin_amdgcn_exp2f(l0 - mx), w1 = __builtin_amdgcn_exp2f(l1 - mx), w2 = __builtin_amdgcn_exp2f(l2 - mx);
;         const float inv = 1.f / (w0 + w1 + w2); w0 *= inv; w1 *= inv; w2 *= inv;
;         const v4u a0 = *(const v4u*)(OBG + tok * 256 + part * 8), a1 = *(const v4u*)(OBG + ((size_t)TT + tok) * 256 + part * 8), a2 = *(const v4u*)(OBG + ((size_t)2 * TT + tok) * 256 + part * 8);
;         w0 *= 8.f; w1 *= 8.f; w2 *= 8.f;
;         v2u o;
;         o.x = pk4_fp8(w0 * bf_lo(a0.x) + w1 * bf_lo(a1.x) + w2 * bf_lo(a2.x), w0 * bf_hi(a0.x) + w1 * bf_hi(a1.x) + w2 * bf_hi(a2.x), w0 * bf_lo(a0.y) + w1 * bf_lo(a1.y) + w2 * bf_lo(a2.y), w0 * bf_hi(a0.y) + w1 * bf_hi(a1.y) + w2 * bf_hi(a2.y));
;         o.y = pk4_fp8(w0 * bf_lo(a0.z) + w1 * bf_lo(a1.z) + w2 * bf_lo(a2.z), w0 * bf_hi(a0.z) + w1 * bf_hi(a1.z) + w2 * bf_hi(a2.z), w0 * bf_lo(a0.w) + w1 * bf_lo(a1.w) + w2 * bf_lo(a2.w), w0 * bf_hi(a0.w) + w1 * bf_hi(a1.w) + w2 * bf_hi(a2.w));
;         *(v2u*)((unsigned char*)OA + tok * 768 + 512 + part * 8) = o;
;     }
.LBB0_272:
	s_or_b64 exec, exec, s[4:5]
	s_barrier
	s_lshl_b32 s40, s2, 9
	s_mov_b32 s41, 0x280000
	s_mov_b64 s[2:3], exec
	s_cmp_ge_u32 s40, s41
	s_cbranch_scc1 .LBB0_275
	v_lshrrev_b32_e32 v61, 1, v254
	v_and_b32_e32 v61, 12, v61
	v_and_b32_e32 v4, 31, v254
	v_lshlrev_b32_e32 v62, 4, v4
	v_lshrrev_b32_e32 v60, 5, v254
	v_mov_b32_e32 v1, 0
	v_lshlrev_b32_e32 v0, 3, v4
	v_lshl_add_u64 v[6:7], s[16:17], 0, v[0:1]
	s_lshl_b32 s7, s24, 9
	s_mov_b32 s6, 0x41000000
	s_movk_i32 s8, 0x300
	s_lshr_b32 s45, s40, 5
	v_add_u32_e32 v73, s45, v60
	v_lshl_add_u32 v64, v73, 4, v61
	v_add_u32_e32 v65, 0x140000, v64
	v_add_u32_e32 v66, 0x280000, v64
	v_lshl_add_u32 v67, v73, 9, v62
	v_add_u32_e32 v68, 0x2800000, v67
	v_add_u32_e32 v69, 0x5000000, v67
	global_load_dword v70, v64, s[14:15]
	global_load_dword v71, v65, s[14:15]
	global_load_dword v72, v66, s[14:15]
	global_load_dwordx4 v[76:79], v68, s[20:21]
	global_load_dwordx4 v[80:83], v67, s[20:21]
	global_load_dwordx4 v[84:87], v69, s[20:21]
	s_add_u32 s46, s40, s7
	s_cmp_lt_u32 s46, s41
	s_cbranch_scc0 .Lmy_p2b_loop
	s_lshr_b32 s45, s46, 5
	v_add_u32_e32 v93, s45, v60
	v_lshl_add_u32 v64, v93, 4, v61
	v_add_u32_e32 v65, 0x140000, v64
	v_add_u32_e32 v66, 0x280000, v64
	v_lshl_add_u32 v67, v93, 9, v62
	v_add_u32_e32 v68, 0x2800000, v67
	v_add_u32_e32 v69, 0x5000000, v67
	global_load_dword v90, v64, s[14:15]
	global_load_dword v91, v65, s[14:15]
	global_load_dword v92, v66, s[14:15]
	global_load_dwordx4 v[96:99], v68, s[20:21]
	global_load_dwordx4 v[100:103], v67, s[20:21]
	global_load_dwordx4 v[104:107], v69, s[20:21]
.Lmy_p2b_loop:
	s_cmp_ge_u32 s40, s41
	s_cbranch_scc1 .LBB0_275
	s_add_u32 s46, s40, s7
	s_cmp_lt_u32 s46, s41
	s_cbranch_scc1 .Lmy_p2b_w6_0
	s_waitcnt vmcnt(0)
	s_branch .Lmy_p2b_wd_0
.Lmy_p2b_w6_0:
	s_waitcnt vmcnt(6)
.Lmy_p2b_wd_0:
	v_mov_b32_e32 v9, v70
	v_mov_b32_e32 v36, v71
	v_mov_b32_e32 v37, v72
	v_mov_b32_e32 v0, v73
	v_mov_b64_e32 v[10:11], v[76:77]
	v_mov_b64_e32 v[12:13], v[78:79]
	v_mov_b64_e32 v[14:15], v[80:81]
	v_mov_b64_e32 v[16:17], v[82:83]
	v_mov_b64_e32 v[18:19], v[84:85]
	v_mov_b64_e32 v[20:21], v[86:87]
	s_lshl_b32 s47, s7, 1
	s_add_u32 s47, s40, s47
	s_cmp_lt_u32 s47, s41
	s_cbranch_scc0 .Lmy_p2b_np_0
	s_lshr_b32 s45, s47, 5
	v_add_u32_e32 v73, s45, v60
	v_lshl_add_u32 v64, v73, 4, v61
	v_add_u32_e32 v65, 0x140000, v64
	v_add_u32_e32 v66, 0x280000, v64
	v_lshl_add_u32 v67, v73, 9, v62
	v_add_u32_e32 v68, 0x2800000, v67
	v_add_u32_e32 v69, 0x5000000, v67
	global_load_dword v70, v64, s[14:15]
	global_load_dword v71, v65, s[14:15]
	global_load_dword v72, v66, s[14:15]
	global_load_dwordx4 v[76:79], v68, s[20:21]
	global_load_dwordx4 v[80:83], v67, s[20:21]
	global_load_dwordx4 v[84:87], v69, s[20:21]
.Lmy_p2b_np_0:
	v_mov_b32_e32 v22, v1
	v_mov_b32_e32 v23, v1
	v_max3_f32 v32, v9, v36, v37
	v_lshlrev_b32_e32 v35, 16, v11
	v_and_b32_e32 v38, 0xffff0000, v11
	v_lshlrev_b32_e32 v11, 16, v14
	v_and_b32_e32 v25, 0xffff0000, v14
	v_lshlrev_b32_e32 v26, 16, v19
	v_and_b32_e32 v14, 0xffff0000, v19
	v_lshlrev_b32_e32 v19, 16, v16
	v_and_b32_e32 v29, 0xffff0000, v16
	v_sub_f32_e32 v9, v9, v32
	v_sub_f32_e32 v16, v36, v32
	v_lshlrev_b32_e32 v33, 16, v10
	v_and_b32_e32 v34, 0xffff0000, v10
	v_lshlrev_b32_e32 v41, 16, v13
	v_lshlrev_b32_e32 v10, 16, v18
	v_and_b32_e32 v24, 0xffff0000, v18
	v_lshlrev_b32_e32 v18, 16, v20
	v_and_b32_e32 v28, 0xffff0000, v20
	v_lshlrev_b32_e32 v31, 16, v17
	v_and_b32_e32 v42, 0xffff0000, v13
	v_and_b32_e32 v13, 0xffff0000, v17
	v_sub_f32_e32 v20, v37, v32
	v_exp_f32_e32 v17, v9
	v_exp_f32_e32 v9, v16
	v_exp_f32_e32 v16, v20
	v_lshlrev_b32_e32 v39, 16, v12
	v_and_b32_e32 v40, 0xffff0000, v12
	v_add_f32_e32 v20, v17, v9
	v_add_f32_e32 v20, v16, v20
	v_lshlrev_b32_e32 v30, 16, v21
	v_and_b32_e32 v12, 0xffff0000, v21
	v_div_scale_f32 v21, s[0:1], v20, v20, 1.0
	v_rcp_f32_e32 v36, v21
	v_div_scale_f32 v32, vcc, 1.0, v20, 1.0
	v_lshlrev_b32_e32 v27, 16, v15
	v_fma_f32 v37, -v21, v36, 1.0
	v_fmac_f32_e32 v36, v37, v36
	v_mul_f32_e32 v37, v32, v36
	v_fma_f32 v43, -v21, v37, v32
	v_fmac_f32_e32 v37, v43, v36
	v_fma_f32 v21, -v21, v37, v32
	v_div_fmas_f32 v21, v21, v36, v37
	v_div_fixup_f32 v20, v21, v20, 1.0
	v_pk_mul_f32 v[16:17], v[16:17], v[20:21] op_sel_hi:[1,0]
	v_and_b32_e32 v15, 0xffff0000, v15
	v_mul_f32_e32 v9, v9, v20
	v_pk_mul_f32 v[16:17], v[16:17], s[6:7] op_sel_hi:[1,0]
	v_mul_f32_e32 v9, 0x41000000, v9
	v_pk_mul_f32 v[10:11], v[16:17], v[10:11]
	v_pk_mul_f32 v[20:21], v[16:17], v[24:25]
	v_pk_mul_f32 v[24:25], v[16:17], v[26:27]
	v_pk_mul_f32 v[14:15], v[16:17], v[14:15]
	v_pk_mul_f32 v[18:19], v[16:17], v[18:19]
	v_pk_mul_f32 v[26:27], v[16:17], v[28:29]
	v_pk_mul_f32 v[28:29], v[16:17], v[30:31]
	v_pk_mul_f32 v[12:13], v[16:17], v[12:13]
	v_fma_f32 v11, v9, v33, v11
	v_fma_f32 v16, v9, v34, v21
	v_fma_f32 v15, v9, v38, v15
	v_fma_f32 v19, v9, v39, v19
	v_fma_f32 v21, v9, v40, v27
	v_add_f32_e32 v10, v10, v11
	v_add_f32_e32 v11, v20, v16
	v_add_f32_e32 v14, v14, v15
	v_add_f32_e32 v15, v18, v19
	v_add_f32_e32 v16, v26, v21
	v_cvt_pk_fp8_f32 v22, v10, v11
	v_cvt_pk_fp8_f32 v23, v15, v16
	v_fma_f32 v17, v9, v35, v25
	v_fma_f32 v25, v9, v41, v29
	v_fma_f32 v9, v9, v42, v13
	v_add_f32_e32 v13, v24, v17
	v_add_f32_e32 v17, v28, v25
	v_add_f32_e32 v9, v12, v9
	v_cvt_pk_fp8_f32 v22, v13, v14 op_sel:[0,0,1]
	v_cvt_pk_fp8_f32 v23, v17, v9 op_sel:[0,0,1]
	v_mad_u64_u32 v[10:11], s[0:1], v0, s8, v[6:7]
	global_store_dwordx2 v[10:11], v[22:23], off offset:512
	s_add_u32 s40, s40, s7
	s_cmp_ge_u32 s40, s41
	s_cbranch_scc1 .LBB0_275
	s_add_u32 s46, s40, s7
	s_cmp_lt_u32 s46, s41
	s_cbranch_scc1 .Lmy_p2b_w6_1
	s_waitcnt vmcnt(0)
	s_branch .Lmy_p2b_wd_1

; __device__ __forceinline__ unsigned pk4_fp8(float a, float b, float c, float d) { int r = __builtin_amdgcn_cvt_pk_fp8_f32(a, b, 0, false); r = __builtin_amdgcn_cvt_pk_fp8_f32(c, d, r, true); return (unsigned)r; }
; __global__ void __launch_bounds__(512, 2) mk_fwd(Args a) {
;     ...
;     for (unsigned idx = (unsigned)bx * 512u + (unsigned)threadIdx.x; idx < (unsigned)TT * 32u; idx += (unsigned)G * 512u) {
;         const size_t tok = idx >> 5; const int part = (int)(idx & 31u), hh = part >> 3;
;         const float l0 = LSE[tok * 4 + hh], l1 = LSE[((size_t)TT + tok) * 4 + hh], l2 = LSE[((size_t)2 * TT + tok) * 4 + hh];
;         const float mx = fmaxf(l0, fmaxf(l1, l2)); float w0 = __builtin_amdgcn_exp2f(l0 - mx), w1 = __builtin_amdgcn_exp2f(l1 - mx), w2 = __builtin_amdgcn_exp2f(l2 - mx);
;         const float inv = 1.f / (w0 + w1 + w2); w0 *= inv; w1 *= inv; w2 *= inv;
;         const v4u a0 = *(const v4u*)(OBG + tok * 256 + part * 8), a1 = *(const v4u*)(OBG + ((size_t)TT + tok) * 256 + part * 8), a2 = *(const v4u*)(OBG + ((size_t)2 * TT + tok) * 256 + part * 8);
;         w0 *= 8.f; w1 *= 8.f; w2 *= 8.f;
;         v2u o;
;         o.x = pk4_fp8(w0 * bf_lo(a0.x) + w1 * bf_lo(a1.x) + w2 * bf_lo(a2.x), w0 * bf_hi(a0.x) + w1 * bf_hi(a1.x) + w2 * bf_hi(a2.x), w0 * bf_lo(a0.y) + w1 * bf_lo(a1.y) + w2 * bf_lo(a2.y), w0 * bf_hi(a0.y) + w1 * bf_hi(a1.y) + w2 * bf_hi(a2.y));
;         o.y = pk4_fp8(w0 * bf_lo(a0.z) + w1 * bf_lo(a1.z) + w2 * bf_lo(a2.z), w0 * bf_hi(a0.z) + w1 * bf_hi(a1.z) + w2 * bf_hi(a2.z), w0 * bf_lo(a0.w) + w1 * bf_lo(a1.w) + w2 * bf_lo(a2.w), w0 * bf_hi(a0.w) + w1 * bf_hi(a1.w) + w2 * bf_hi(a2.w));
;         *(v2u*)((unsigned char*)OA + tok * 768 + 512 + part * 8) = o;
;     }
.Lmy_p2b_wd_1:
	v_mov_b32_e32 v9, v90
	v_mov_b32_e32 v36, v91
	v_mov_b32_e32 v37, v92
	v_mov_b32_e32 v0, v93
	v_mov_b64_e32 v[10:11], v[96:97]
	v_mov_b64_e32 v[12:13], v[98:99]
	v_mov_b64_e32 v[14:15], v[100:101]
	v_mov_b64_e32 v[16:17], v[102:103]
	v_mov_b64_e32 v[18:19], v[104:105]
	v_mov_b64_e32 v[20:21], v[106:107]
	s_lshl_b32 s47, s7, 1
	s_add_u32 s47, s40, s47
	s_cmp_lt_u32 s47, s41
	s_cbranch_scc0 .Lmy_p2b_np_1
	s_lshr_b32 s45, s47, 5
	v_add_u32_e32 v93, s45, v60
	v_lshl_add_u32 v64, v93, 4, v61
	v_add_u32_e32 v65, 0x140000, v64
	v_add_u32_e32 v66, 0x280000, v64
	v_lshl_add_u32 v67, v93, 9, v62
	v_add_u32_e32 v68, 0x2800000, v67
	v_add_u32_e32 v69, 0x5000000, v67
	global_load_dword v90, v64, s[14:15]
	global_load_dword v91, v65, s[14:15]
	global_load_dword v92, v66, s[14:15]
	global_load_dwordx4 v[96:99], v68, s[20:21]
	global_load_dwordx4 v[100:103], v67, s[20:21]
	global_load_dwordx4 v[104:107], v69, s[20:21]
.Lmy_p2b_np_1:
	v_mov_b32_e32 v22, v1
	v_mov_b32_e32 v23, v1
	v_max3_f32 v32, v9, v36, v37
	v_lshlrev_b32_e32 v35, 16, v11
	v_and_b32_e32 v38, 0xffff0000, v11
	v_lshlrev_b32_e32 v11, 16, v14
	v_and_b32_e32 v25, 0xffff0000, v14
	v_lshlrev_b32_e32 v26, 16, v19
	v_and_b32_e32 v14, 0xffff0000, v19
	v_lshlrev_b32_e32 v19, 16, v16
	v_and_b32_e32 v29, 0xffff0000, v16
	v_sub_f32_e32 v9, v9, v32
	v_sub_f32_e32 v16, v36, v32
	v_lshlrev_b32_e32 v33, 16, v10
	v_and_b32_e32 v34, 0xffff0000, v10
	v_lshlrev_b32_e32 v41, 16, v13
	v_lshlrev_b32_e32 v10, 16, v18
	v_and_b32_e32 v24, 0xffff0000, v18
	v_lshlrev_b32_e32 v18, 16, v20
	v_and_b32_e32 v28, 0xffff0000, v20
	v_lshlrev_b32_e32 v31, 16, v17
	v_and_b32_e32 v42, 0xffff0000, v13
	v_and_b32_e32 v13, 0xffff0000, v17
	v_sub_f32_e32 v20, v37, v32
	v_exp_f32_e32 v17, v9
	v_exp_f32_e32 v9, v16
	v_exp_f32_e32 v16, v20
	v_lshlrev_b32_e32 v39, 16, v12
	v_and_b32_e32 v40, 0xffff0000, v12
	v_add_f32_e32 v20, v17, v9
	v_add_f32_e32 v20, v16, v20
	v_lshlrev_b32_e32 v30, 16, v21
	v_and_b32_e32 v12, 0xffff0000, v21
	v_div_scale_f32 v21, s[0:1], v20, v20, 1.0
	v_rcp_f32_e32 v36, v21
	v_div_scale_f32 v32, vcc, 1.0, v20, 1.0
	v_lshlrev_b32_e32 v27, 16, v15
	v_fma_f32 v37, -v21, v36, 1.0
	v_fmac_f32_e32 v36, v37, v36
	v_mul_f32_e32 v37, v32, v36
	v_fma_f32 v43, -v21, v37, v32
	v_fmac_f32_e32 v37, v43, v36
	v_fma_f32 v21, -v21, v37, v32
	v_div_fmas_f32 v21, v21, v36, v37
	v_div_fixup_f32 v20, v21, v20, 1.0
	v_pk_mul_f32 v[16:17], v[16:17], v[20:21] op_sel_hi:[1,0]
	v_and_b32_e32 v15, 0xffff0000, v15
	v_mul_f32_e32 v9, v9, v20
	v_pk_mul_f32 v[16:17], v[16:17], s[6:7] op_sel_hi:[1,0]
	v_mul_f32_e32 v9, 0x41000000, v9
	v_pk_mul_f32 v[10:11], v[16:17], v[10:11]
	v_pk_mul_f32 v[20:21], v[16:17], v[24:25]
	v_pk_mul_f32 v[24:25], v[16:17], v[26:27]
	v_pk_mul_f32 v[14:15], v[16:17], v[14:15]
	v_pk_mul_f32 v[18:19], v[16:17], v[18:19]
	v_pk_mul_f32 v[26:27], v[16:17], v[28:29]
	v_pk_mul_f32 v[28:29], v[16:17], v[30:31]
	v_pk_mul_f32 v[12:13], v[16:17], v[12:13]
	v_fma_f32 v11, v9, v33, v11
	v_fma_f32 v16, v9, v34, v21
	v_fma_f32 v15, v9, v38, v15
	v_fma_f32 v19, v9, v39, v19
	v_fma_f32 v21, v9, v40, v27
	v_add_f32_e32 v10, v10, v11
	v_add_f32_e32 v11, v20, v16
	v_add_f32_e32 v14, v14, v15
	v_add_f32_e32 v15, v18, v19
	v_add_f32_e32 v16, v26, v21
	v_cvt_pk_fp8_f32 v22, v10, v11
	v_cvt_pk_fp8_f32 v23, v15, v16
	v_fma_f32 v17, v9, v35, v25
	v_fma_f32 v25, v9, v41, v29
	v_fma_f32 v9, v9, v42, v13
	v_add_f32_e32 v13, v24, v17
	v_add_f32_e32 v17, v28, v25
	v_add_f32_e32 v9, v12, v9
	v_cvt_pk_fp8_f32 v22, v13, v14 op_sel:[0,0,1]
	v_cvt_pk_fp8_f32 v23, v17, v9 op_sel:[0,0,1]
	v_mad_u64_u32 v[10:11], s[0:1], v0, s8, v[6:7]
	global_store_dwordx2 v[10:11], v[22:23], off offset:512
	s_add_u32 s40, s40, s7
	s_branch .Lmy_p2b_loop

; #define PG8_BAR __builtin_amdgcn_s_barrier()
; template <class Epi, class Sched, bool ALIGN_EPI = false, bool SP2 = false, bool FP8 = false>
; __device__ __forceinline__ void gemm_phase(PG8_LAS unsigned char* lds, const Gemm g, const Sched& S, const Epi& E) {
;     ...
;         const char* nA = has_next ? (const char*)g.A + (size_t)nxt.pm * tstep : cA; const char* nB = has_next ? (const char*)g.Bt + (size_t)nxt.pn * tstep : cB;
; #pragma unroll 1
;         for (int t = 0; t < nt; t += 2) {
;             if constexpr (Epi::MID_T > 0) { if (t == Epi::MID_T) E.mid(acc, cur, wr, wc, fr, fq); }
;             const bool last = (t == nt - 2);
;             const char* a1 = cA + (size_t)(t + 1) * kstep;
;             const char* a2 = last ? nA : cA + (size_t)(t + 2) * kstep; const char* b2 = last ? nB : cB + (size_t)(t + 2) * kstep;
;             const char* a3 = a2 + kstep; const char* b3 = b2 + kstep;
;     ...
;         for (int a = 0; a < 2; ++a)
; #pragma unroll
;             for (int b = 0; b < 2; ++b)
; #pragma unroll
;                 for (int m = 0; m < 4; ++m)
; #pragma unroll
;                     for (int n = 0; n < 2; ++n) { acc[a][b][m][n] = (f32x4){0.f, 0.f, 0.f, 0.f}; if constexpr (FP8) asm volatile("" : "+v"(acc[a][b][m][n])); }
;         cur = nxt; cA = nA; cB = nB; ++ui;
;         if constexpr (ALIGN_EPI) { if (wr == 1) PG8_BAR; }
.LBB0_390:
	s_ashr_i32 s15, s14, 31
	s_lshl_b64 s[0:1], s[14:15], 19
	s_add_u32 s34, s16, s0
	s_addc_u32 s35, s17, s1
	s_and_b64 s[0:1], s[4:5], exec
	s_cselect_b32 s15, s35, s41
	s_cselect_b32 s57, s34, s40
	s_ashr_i32 s13, s12, 31
	s_lshl_b64 s[0:1], s[12:13], 19
	s_add_u32 s36, s30, s0
	s_addc_u32 s37, s31, s1
	s_and_b64 s[0:1], s[4:5], exec
	s_cselect_b32 s13, s37, s43
	s_cselect_b32 s58, s36, s42
	s_add_u32 s40, s40, 0x40080
	s_addc_u32 s41, s41, 0
	s_add_u32 s59, s42, 0x100
	v_mov_b32_e32 v0, 0
	s_addc_u32 s60, s43, 0
	s_mov_b32 s61, -2
	v_mov_b32_e32 v1, v0
	v_mov_b64_e32 v[2:3], v[0:1]
	v_mov_b64_e32 v[4:5], v[0:1]
	v_mov_b64_e32 v[6:7], v[0:1]
	v_mov_b64_e32 v[16:17], v[0:1]
	v_mov_b64_e32 v[18:19], v[0:1]
	v_mov_b64_e32 v[20:21], v[0:1]
	v_mov_b64_e32 v[22:23], v[0:1]
	v_mov_b64_e32 v[32:33], v[0:1]
	v_mov_b64_e32 v[34:35], v[0:1]
	v_mov_b64_e32 v[36:37], v[0:1]
	v_mov_b64_e32 v[38:39], v[0:1]
	v_mov_b64_e32 v[48:49], v[0:1]
	v_mov_b64_e32 v[50:51], v[0:1]
	v_mov_b64_e32 v[52:53], v[0:1]
	v_mov_b64_e32 v[54:55], v[0:1]
	v_mov_b64_e32 v[8:9], v[0:1]
	v_mov_b64_e32 v[10:11], v[0:1]
	v_mov_b64_e32 v[12:13], v[0:1]
	v_mov_b64_e32 v[14:15], v[0:1]
	v_mov_b64_e32 v[24:25], v[0:1]
	v_mov_b64_e32 v[26:27], v[0:1]
	v_mov_b64_e32 v[28:29], v[0:1]
	v_mov_b64_e32 v[30:31], v[0:1]
	v_mov_b64_e32 v[40:41], v[0:1]
	v_mov_b64_e32 v[42:43], v[0:1]
	v_mov_b64_e32 v[44:45], v[0:1]
	v_mov_b64_e32 v[46:47], v[0:1]
	v_mov_b64_e32 v[56:57], v[0:1]
	v_mov_b64_e32 v[58:59], v[0:1]
	v_mov_b64_e32 v[60:61], v[0:1]
	v_mov_b64_e32 v[62:63], v[0:1]
	v_mov_b64_e32 v[64:65], v[0:1]
	v_mov_b64_e32 v[66:67], v[0:1]
	v_mov_b64_e32 v[68:69], v[0:1]
	v_mov_b64_e32 v[70:71], v[0:1]
	v_mov_b64_e32 v[80:81], v[0:1]
	v_mov_b64_e32 v[82:83], v[0:1]
	v_mov_b64_e32 v[84:85], v[0:1]
	v_mov_b64_e32 v[86:87], v[0:1]
	v_mov_b64_e32 v[96:97], v[0:1]
	v_mov_b64_e32 v[98:99], v[0:1]
	v_mov_b64_e32 v[100:101], v[0:1]
	v_mov_b64_e32 v[102:103], v[0:1]
	v_mov_b64_e32 v[112:113], v[0:1]
	v_mov_b64_e32 v[114:115], v[0:1]
	v_mov_b64_e32 v[116:117], v[0:1]
	v_mov_b64_e32 v[118:119], v[0:1]
	v_mov_b64_e32 v[72:73], v[0:1]
	v_mov_b64_e32 v[74:75], v[0:1]
	v_mov_b64_e32 v[76:77], v[0:1]
	v_mov_b64_e32 v[78:79], v[0:1]
	v_mov_b64_e32 v[88:89], v[0:1]
	v_mov_b64_e32 v[90:91], v[0:1]
	v_mov_b64_e32 v[92:93], v[0:1]
	v_mov_b64_e32 v[94:95], v[0:1]
	v_mov_b64_e32 v[104:105], v[0:1]
	v_mov_b64_e32 v[106:107], v[0:1]
	v_mov_b64_e32 v[108:109], v[0:1]
	v_mov_b64_e32 v[110:111], v[0:1]
	v_mov_b64_e32 v[120:121], v[0:1]
	v_mov_b64_e32 v[122:123], v[0:1]
	v_mov_b64_e32 v[124:125], v[0:1]
	v_mov_b64_e32 v[126:127], v[0:1]
	s_cmp_eq_u32 s100, 0
	s_cbranch_scc1 .Lmy_nobar_P5
	s_barrier
	s_mov_b32 s100, 0

; #define PG8_BAR __builtin_amdgcn_s_barrier()
; template <class Epi, class Sched, bool ALIGN_EPI = false, bool SP2 = false, bool FP8 = false>
; __device__ __forceinline__ void gemm_phase(PG8_LAS unsigned char* lds, const Gemm g, const Sched& S, const Epi& E) {
;     ...
;         const char* nA = has_next ? (const char*)g.A + (size_t)nxt.pm * tstep : cA; const char* nB = has_next ? (const char*)g.Bt + (size_t)nxt.pn * tstep : cB;
; #pragma unroll 1
;         for (int t = 0; t < nt; t += 2) {
;             if constexpr (Epi::MID_T > 0) { if (t == Epi::MID_T) E.mid(acc, cur, wr, wc, fr, fq); }
;             const bool last = (t == nt - 2);
;             const char* a1 = cA + (size_t)(t + 1) * kstep;
;             const char* a2 = last ? nA : cA + (size_t)(t + 2) * kstep; const char* b2 = last ? nB : cB + (size_t)(t + 2) * kstep;
;             const char* a3 = a2 + kstep; const char* b3 = b2 + kstep;
;     ...
;         for (int a = 0; a < 2; ++a)
; #pragma unroll
;             for (int b = 0; b < 2; ++b)
; #pragma unroll
;                 for (int m = 0; m < 4; ++m)
; #pragma unroll
;                     for (int n = 0; n < 2; ++n) { acc[a][b][m][n] = (f32x4){0.f, 0.f, 0.f, 0.f}; if constexpr (FP8) asm volatile("" : "+v"(acc[a][b][m][n])); }
;         cur = nxt; cA = nA; cB = nB; ++ui;
;         if constexpr (ALIGN_EPI) { if (wr == 1) PG8_BAR; }
.LBB0_426:
	s_ashr_i32 s31, s30, 31
	s_lshl_b64 s[34:35], s[30:31], 21
	s_add_u32 s34, s28, s34
	s_addc_u32 s35, s29, s35
	s_and_b64 s[36:37], s[4:5], exec
	s_cselect_b32 s31, s35, s41
	s_cselect_b32 s39, s34, s40
	s_ashr_i32 s23, s22, 31
	s_lshl_b64 s[36:37], s[22:23], 21
	s_add_u32 s36, s26, s36
	s_addc_u32 s37, s27, s37
	s_and_b64 s[44:45], s[4:5], exec
	s_cselect_b32 s23, s37, s43
	s_cselect_b32 s60, s36, s42
	s_add_u32 s40, s40, 0x100080
	s_addc_u32 s41, s41, 0
	s_add_u32 s61, s42, 0x100
	v_mov_b32_e32 v0, 0
	s_addc_u32 s62, s43, 0
	s_mov_b32 s63, -2
	v_mov_b32_e32 v1, v0
	v_mov_b64_e32 v[2:3], v[0:1]
	v_mov_b64_e32 v[4:5], v[0:1]
	v_mov_b64_e32 v[6:7], v[0:1]
	v_mov_b64_e32 v[16:17], v[0:1]
	v_mov_b64_e32 v[18:19], v[0:1]
	v_mov_b64_e32 v[20:21], v[0:1]
	v_mov_b64_e32 v[22:23], v[0:1]
	v_mov_b64_e32 v[32:33], v[0:1]
	v_mov_b64_e32 v[34:35], v[0:1]
	v_mov_b64_e32 v[36:37], v[0:1]
	v_mov_b64_e32 v[38:39], v[0:1]
	v_mov_b64_e32 v[48:49], v[0:1]
	v_mov_b64_e32 v[50:51], v[0:1]
	v_mov_b64_e32 v[52:53], v[0:1]
	v_mov_b64_e32 v[54:55], v[0:1]
	v_mov_b64_e32 v[8:9], v[0:1]
	v_mov_b64_e32 v[10:11], v[0:1]
	v_mov_b64_e32 v[12:13], v[0:1]
	v_mov_b64_e32 v[14:15], v[0:1]
	v_mov_b64_e32 v[24:25], v[0:1]
	v_mov_b64_e32 v[26:27], v[0:1]
	v_mov_b64_e32 v[28:29], v[0:1]
	v_mov_b64_e32 v[30:31], v[0:1]
	v_mov_b64_e32 v[40:41], v[0:1]
	v_mov_b64_e32 v[42:43], v[0:1]
	v_mov_b64_e32 v[44:45], v[0:1]
	v_mov_b64_e32 v[46:47], v[0:1]
	v_mov_b64_e32 v[56:57], v[0:1]
	v_mov_b64_e32 v[58:59], v[0:1]
	v_mov_b64_e32 v[60:61], v[0:1]
	v_mov_b64_e32 v[62:63], v[0:1]
	v_mov_b64_e32 v[64:65], v[0:1]
	v_mov_b64_e32 v[66:67], v[0:1]
	v_mov_b64_e32 v[68:69], v[0:1]
	v_mov_b64_e32 v[70:71], v[0:1]
	v_mov_b64_e32 v[80:81], v[0:1]
	v_mov_b64_e32 v[82:83], v[0:1]
	v_mov_b64_e32 v[84:85], v[0:1]
	v_mov_b64_e32 v[86:87], v[0:1]
	v_mov_b64_e32 v[96:97], v[0:1]
	v_mov_b64_e32 v[98:99], v[0:1]
	v_mov_b64_e32 v[100:101], v[0:1]
	v_mov_b64_e32 v[102:103], v[0:1]
	v_mov_b64_e32 v[112:113], v[0:1]
	v_mov_b64_e32 v[114:115], v[0:1]
	v_mov_b64_e32 v[116:117], v[0:1]
	v_mov_b64_e32 v[118:119], v[0:1]
	v_mov_b64_e32 v[72:73], v[0:1]
	v_mov_b64_e32 v[74:75], v[0:1]
	v_mov_b64_e32 v[76:77], v[0:1]
	v_mov_b64_e32 v[78:79], v[0:1]
	v_mov_b64_e32 v[88:89], v[0:1]
	v_mov_b64_e32 v[90:91], v[0:1]
	v_mov_b64_e32 v[92:93], v[0:1]
	v_mov_b64_e32 v[94:95], v[0:1]
	v_mov_b64_e32 v[104:105], v[0:1]
	v_mov_b64_e32 v[106:107], v[0:1]
	v_mov_b64_e32 v[108:109], v[0:1]
	v_mov_b64_e32 v[110:111], v[0:1]
	v_mov_b64_e32 v[120:121], v[0:1]
	v_mov_b64_e32 v[122:123], v[0:1]
	v_mov_b64_e32 v[124:125], v[0:1]
	v_mov_b64_e32 v[126:127], v[0:1]
	s_cmp_eq_u32 s100, 0
	s_cbranch_scc1 .Lmy_nobar_P6
	s_barrier
	s_mov_b32 s100, 0
